# P4 main GEMM K-loop: LDS-DMA issue rebalanced between load segments (4/4/4/4 instead of 2/6/2/6), counted waits 10/4
# speedup vs baseline: 1.0065x; 1.0065x over previous
;     __device__ __forceinline__ bool next(int i, Unit& u) const { const int L = L0 + i * G + c; if (L >= L1) return false; u.pm = L >> 2; u.pn = L & 3; u.ko = 0; return true; }
; #define PG8_WAIT_V(n) asm volatile("s_waitcnt vmcnt(" #n ")" ::: "memory")
; #define PG8_BAR __builtin_amdgcn_s_barrier()
; template <class Epi, class Sched, bool ALIGN_EPI = false, bool SP2 = false, bool HALFM = false>
; __device__ __forceinline__ void gemm_phase(PG8_LAS unsigned char* lds, const Gemm g, const Sched& S, const Epi& E) {
;     ...
;     const int tid = tid_, wid = __builtin_amdgcn_readfirstlane(tid >> 6), lane = tid & 63, wr = wid >> 2, wc = wid & 3, fr = lane & 15, fq = lane >> 4;
;     const int K = g.K, nt = K / BK;
;     unsigned voffA[2], voffB[2];
; #pragma unroll
;     for (int i = 0; i < 2; ++i) { int R, C; stage_rc(tid * 16 + i * 8192, R, C); const int Rb = Epi::PERM ? ((R & ~31) + perm32(R & 31)) : R;
;         voffA[i] = (unsigned)(R * g.ld + C) * 2u; voffB[i] = (unsigned)(Rb * g.ld + C) * 2u; }
;     const size_t kstep = (size_t)(BK * 2);
;     const size_t hstep = (size_t)HALF * g.ld * 2;
;     const size_t tstep = 2 * hstep;
;     const unsigned ldsw = (unsigned)wid * 1024u;
;     const int aoff = lds_byte(wr * 64 + fr, fq * 8), boff = lds_byte(wc * 32 + fr, fq * 8);
;     ...
;     Unit cur, nxt; int ui = 0;
;     if (!S.next(0, cur)) return;
;     f32x4 acc[2][2][4][2];
; #pragma unroll
;     for (int a = 0; a < 2; ++a)
; #pragma unroll
;         for (int b = 0; b < 2; ++b)
; #pragma unroll
;             for (int m = 0; m < 4; ++m)
; #pragma unroll
;                 for (int n = 0; n < 2; ++n) acc[a][b][m][n] = (f32x4){0.f, 0.f, 0.f, 0.f};
;     bf16x8 At[4][2], B0[2][2], B1[2][2];
;     const char* cA = (const char*)g.A + (size_t)cur.pm * tstep + (size_t)cur.ko * 2; const char* cB = (const char*)g.Bt + (size_t)cur.pn * tstep + (size_t)cur.ko * 2;
;     S.a_ready(cur);
;     if constexpr (SP2) {
;         PG8_STAGE(PG8_SB(0, 0), cB, voffB); PG8_STAGE(PG8_SB(0, 1), cB + hstep, voffB); PG8_STAGE(PG8_SA(0, 0), cA, voffA); PG8_STAGE(PG8_SA(0, 1), cA + hstep, voffA);
;         if (wr == 1) PG8_BAR;
;         PG8_WAIT_V(2); PG8_BAR;
;         PG8_STAGE(PG8_SB(1, 0), cB + kstep, voffB); PG8_STAGE(PG8_SA(1, 0), cA + kstep, voffA); PG8_STAGE(PG8_SB(1, 1), cB + hstep + kstep, voffB);
;         PG8_WAIT_V(6); PG8_BAR;
.LBB0_743:
	v_readlane_b32 s2, v254, 2
	v_readlane_b32 s3, v254, 3
	s_load_dwordx2 s[16:17], s[2:3], 0x88
	s_add_u32 s46, s96, 0x1200000
	s_addc_u32 s47, s97, 0
	s_andn2_b64 vcc, exec, s[6:7]
	s_cbranch_vccnz .LBB0_908
	v_ashrrev_i32_e32 v2, 31, v10
	v_lshrrev_b32_e32 v2, 26, v2
	v_add_u32_e32 v2, v10, v2
	v_ashrrev_i32_e32 v11, 6, v2
	v_bfe_i32 v2, v10, 27, 1
	v_lshlrev_b32_e32 v1, 4, v10
	v_lshrrev_b32_e32 v2, 22, v2
	v_add_u32_e32 v2, v1, v2
	v_and_b32_e32 v2, 0xfffffc00, v2
	v_sub_u32_e32 v2, v1, v2
	v_lshrrev_b32_e32 v3, 4, v2
	v_bitop3_b32 v2, v3, v2, 32 bitop3:0x6c
	v_ashrrev_i32_e32 v4, 31, v2
	v_lshrrev_b32_e32 v4, 26, v4
	v_add_u32_e32 v4, v2, v4
	v_lshlrev_b32_e32 v3, 3, v11
	v_ashrrev_i32_e32 v12, 6, v4
	v_and_b32_e32 v4, 0xc0, v4
	v_and_b32_e32 v3, -16, v3
	v_sub_u32_e32 v2, v2, v4
	v_mov_b32_e32 v4, 1
	v_add_u32_e32 v3, v12, v3
	v_ashrrev_i16_sdwa v2, v4, sext(v2) dst_sel:DWORD dst_unused:UNUSED_PAD src0_sel:DWORD src1_sel:BYTE_0
	v_lshlrev_b32_e32 v5, 5, v11
	s_waitcnt lgkmcnt(0)
	v_bfe_i32 v13, v2, 0, 16
	v_lshlrev_b32_e32 v2, 1, v3
	v_lshrrev_b32_e32 v6, 2, v3
	v_and_b32_e32 v7, 3, v12
	s_mov_b32 s2, 0x1fffe0
	v_and_b32_e32 v5, 32, v5
	v_and_b32_e32 v2, 24, v2
	v_and_b32_e32 v6, 4, v6
	v_and_or_b32 v7, v3, s2, v7
	v_or3_b32 v2, v7, v6, v2
	v_add_lshl_u32 v5, v5, v13, 1
	v_add_u32_e32 v1, 0x2000, v1
	v_lshl_add_u32 v140, v2, 11, v5
	v_ashrrev_i32_e32 v2, 31, v1
	v_lshrrev_b32_e32 v2, 22, v2
	v_add_u32_e32 v2, v1, v2
	v_ashrrev_i32_e32 v14, 10, v2
	v_mul_i32_i24_e32 v2, 0x400, v14
	v_sub_u32_e32 v1, v1, v2
	v_lshrrev_b32_e32 v2, 4, v1
	v_bitop3_b32 v1, v2, v1, 32 bitop3:0x6c
	v_lshl_add_u32 v138, v3, 11, v5
	v_ashrrev_i32_e32 v3, 31, v1
	v_lshrrev_b32_e32 v3, 26, v3
	v_add_u32_e32 v3, v1, v3
	v_lshlrev_b32_e32 v2, 3, v14
	v_ashrrev_i32_e32 v15, 6, v3
	v_and_b32_e32 v3, 0xc0, v3
	v_and_b32_e32 v2, -16, v2
	v_sub_u32_e32 v1, v1, v3
	s_ashr_i32 s1, s0, 6
	v_add_u32_e32 v2, v15, v2
	v_ashrrev_i16_sdwa v1, v4, sext(v1) dst_sel:DWORD dst_unused:UNUSED_PAD src0_sel:DWORD src1_sel:BYTE_0
	v_and_b32_e32 v4, 3, v15
	s_ashr_i32 s5, s4, 31
	s_ashr_i32 s11, s10, 31
	v_and_or_b32 v4, v2, s2, v4
	s_ashr_i32 s2, s0, 8
	s_lshl_b32 s27, s1, 10
	s_lshl_b64 s[6:7], s[4:5], 19
	s_lshl_b64 s[8:9], s[10:11], 19
	s_add_u32 s38, s46, s8
	v_lshlrev_b32_e32 v5, 5, v14
	v_bfe_i32 v16, v1, 0, 16
	v_lshlrev_b32_e32 v1, 1, v2
	v_lshrrev_b32_e32 v3, 2, v2
	s_addc_u32 s39, s47, s9
	s_add_i32 s44, s27, 0
	v_and_b32_e32 v5, 32, v5
	v_and_b32_e32 v1, 24, v1
	v_and_b32_e32 v3, 4, v3
	s_add_i32 m0, s44, 0x10000
	v_or3_b32 v1, v4, v3, v1
	v_add_lshl_u32 v3, v5, v16, 1
	global_load_lds_dwordx4 v140, s[38:39]
	s_add_i32 m0, s44, 0x12000
	v_lshl_add_u32 v144, v1, 11, v3
	s_add_u32 s8, s38, 0x40000
	global_load_lds_dwordx4 v144, s[38:39]
	s_addc_u32 s9, s39, 0
	s_add_i32 m0, s44, 0x14000
	v_lshl_add_u32 v142, v2, 11, v3
	global_load_lds_dwordx4 v140, s[8:9]
	s_add_i32 m0, s44, 0x16000
	v_mov_b32_e32 v147, 0
	global_load_lds_dwordx4 v144, s[8:9]
	s_add_u32 s8, s80, s6
	s_addc_u32 s9, s81, s7
	s_add_i32 s45, s44, 0x2000
	s_mov_b32 m0, s44
	s_add_u32 s6, s8, 0x40000
	global_load_lds_dwordx4 v138, s[8:9]
	s_mov_b32 m0, s45
	s_addc_u32 s7, s9, 0
	s_add_i32 s48, s44, 0x4000
	global_load_lds_dwordx4 v142, s[8:9]
	s_mov_b32 m0, s48
	s_add_i32 s49, s44, 0x6000
	global_load_lds_dwordx4 v138, s[6:7]
	s_mov_b32 m0, s49
	v_mov_b32_e32 v141, v147
	global_load_lds_dwordx4 v142, s[6:7]
	v_mov_b32_e32 v145, v147
	v_mov_b32_e32 v139, v147
	v_mov_b32_e32 v143, v147
	s_cmp_eq_u32 s2, 1
	s_mov_b32 s50, 0
	s_mov_b32 s51, 0x10000
	v_lshl_add_u64 v[8:9], s[38:39], 0, v[140:141]
	v_lshl_add_u64 v[6:7], s[38:39], 0, v[144:145]
	v_lshl_add_u64 v[2:3], s[8:9], 0, v[138:139]
	s_cselect_b64 s[18:19], -1, 0
	s_cmp_lg_u32 s2, 1
	v_lshl_add_u64 v[4:5], s[8:9], 0, v[142:143]
	v_lshl_add_u64 v[228:229], s[8:9], 0, v[138:139]
	v_lshl_add_u64 v[230:231], s[8:9], 0, v[142:143]
	s_cbranch_scc1 .LBB0_746
	s_barrier

;     __device__ __forceinline__ bool next(int i, Unit& u) const { const int L = L0 + i * G + c; if (L >= L1) return false; u.pm = L >> 2; u.pn = L & 3; u.ko = 0; return true; }
; #define PG8_STAGE(bufoff, gbase, voff) do { _Pragma("unroll") for (int _i = 0; _i < 2; ++_i) \
;         __builtin_amdgcn_global_load_lds((const unsigned*)((const char*)(gbase) + (voff)[_i]), (PG8_LAS unsigned*)(lds + (bufoff) + ldsw + _i * 8192), 16, 0, 0); } while (0)
; #define PG8_LDA(dst, b, h) do { _Pragma("unroll") for (int m = 0; m < 4; ++m) _Pragma("unroll") for (int k = 0; k < 2; ++k) dst[m][k] = *(const PG8_LAS bf16x8*)(lds + PG8_SA(b, h) + aoff + m * 2048 + k * 1024); } while (0)
; #define PG8_LDB(dst, b, h) do { _Pragma("unroll") for (int n = 0; n < 2; ++n) _Pragma("unroll") for (int k = 0; k < 2; ++k) dst[n][k] = *(const PG8_LAS bf16x8*)(lds + PG8_SB(b, h) + boff + n * 2048 + k * 1024); } while (0)
; #define PG8_WAIT_V(n) asm volatile("s_waitcnt vmcnt(" #n ")" ::: "memory")
; #define PG8_WAIT_L(n) asm volatile("s_waitcnt lgkmcnt(" #n ")" ::: "memory")
; template <class Epi, class Sched, bool ALIGN_EPI = false, bool SP2 = false, bool HALFM = false>
; __device__ __forceinline__ void gemm_phase(PG8_LAS unsigned char* lds, const Gemm g, const Sched& S, const Epi& E) {
;     ...
;         const bool has_next = S.next(ui + 1, nxt);
;         const char* nA = has_next ? (const char*)g.A + (size_t)nxt.pm * tstep + (size_t)nxt.ko * 2 : cA; const char* nB = has_next ? (const char*)g.Bt + (size_t)nxt.pn * tstep + (size_t)nxt.ko * 2 : cB;
;         for (int t = 0; t < nt; t += 2) {
;             const bool last = (t == nt - 2);
;             const char* a1 = cA + (size_t)(t + 1) * kstep;
;             const char* a2 = last ? nA : cA + (size_t)(t + 2) * kstep; const char* b2 = last ? nB : cB + (size_t)(t + 2) * kstep;
;             const char* a3 = a2 + kstep; const char* b3 = b2 + kstep;
;             if (last && has_next) S.a_ready(nxt);
;             if constexpr (SP2) {
;             PG8_LDB(B0, 0, 0); PG8_LDB(B1, 0, 1); PG8_SCHED; PG8_LDA(At, 0, 0); PG8_STAGE(PG8_SA(1, 1), a1 + hstep, voffA);
;             PG8_WAIT_V(8); PG8_WAIT_L(0); PG8_BAR; PG8_MMA(0, 0, At, B0); PG8_MMA(0, 1, At, B1); PG8_BAR; PG8_SCHED;
;             PG8_LDA(At, 0, 1); PG8_STAGE(PG8_SB(0, 0), b2, voffB); PG8_STAGE(PG8_SB(0, 1), b2 + hstep, voffB); PG8_STAGE(PG8_SA(0, 0), a2, voffA);
.LBB0_752:
	s_waitcnt lgkmcnt(0)
	ds_read_b128 v[82:85], v190
	ds_read_b128 v[134:137], v190 offset:1024
	ds_read_b128 v[160:163], v190 offset:2048
	ds_read_b128 v[164:167], v190 offset:3072
	ds_read_b128 v[168:171], v191
	ds_read_b128 v[172:175], v191 offset:1024
	ds_read_b128 v[176:179], v191 offset:2048
	ds_read_b128 v[180:183], v191 offset:3072
	s_add_u32 s31, s8, 0xfffc0080
	s_addc_u32 s38, s9, -1
	s_cmp_eq_u32 s29, 12
	s_cselect_b32 s41, s0, s38
	s_cselect_b32 s40, s1, s31
	s_cselect_b32 s39, s2, s11
	s_cselect_b32 s38, s3, s5
	v_lshl_add_u64 v[224:225], s[8:9], 0, v[152:153]
	s_add_i32 m0, s44, 0xc000
	ds_read_b128 v[184:187], v192
	ds_read_b128 v[196:199], v192 offset:1024
	ds_read_b128 v[200:203], v192 offset:2048
	ds_read_b128 v[204:207], v192 offset:3072
	ds_read_b128 v[208:211], v192 offset:4096
	ds_read_b128 v[212:215], v192 offset:5120
	ds_read_b128 v[216:219], v192 offset:6144
	ds_read_b128 v[220:223], v192 offset:7168
	global_load_lds_dwordx4 v[224:225], off
	v_lshl_add_u64 v[224:225], s[8:9], 0, v[154:155]
	s_add_i32 m0, s44, 0xe000
	s_nop 0
	global_load_lds_dwordx4 v[224:225], off
	s_mov_b32 m0, s52
	v_lshl_add_u64 v[224:225], v[228:229], 0, s[20:21]
	global_load_lds_dwordx4 v[224:225], off
	s_mov_b32 m0, s53
	v_lshl_add_u64 v[224:225], v[230:231], 0, s[20:21]
	global_load_lds_dwordx4 v[224:225], off
	s_waitcnt vmcnt(10)
	s_waitcnt lgkmcnt(0)
	s_barrier
	s_setprio 1
	s_waitcnt lgkmcnt(0)
	v_mfma_f32_16x16x32_bf16 v[130:133], v[82:85], v[184:187], v[130:133]
	v_mfma_f32_16x16x32_bf16 v[126:129], v[160:163], v[184:187], v[126:129]
	v_mfma_f32_16x16x32_bf16 v[114:117], v[82:85], v[200:203], v[114:117]
	v_mfma_f32_16x16x32_bf16 v[110:113], v[160:163], v[200:203], v[110:113]
	v_mfma_f32_16x16x32_bf16 v[98:101], v[82:85], v[208:211], v[98:101]
	v_mfma_f32_16x16x32_bf16 v[94:97], v[160:163], v[208:211], v[94:97]
	v_mfma_f32_16x16x32_bf16 v[78:81], v[82:85], v[216:219], v[78:81]
	v_mfma_f32_16x16x32_bf16 v[74:77], v[160:163], v[216:219], v[74:77]
	v_mfma_f32_16x16x32_bf16 v[130:133], v[134:137], v[196:199], v[130:133]
	v_mfma_f32_16x16x32_bf16 v[126:129], v[164:167], v[196:199], v[126:129]
	v_mfma_f32_16x16x32_bf16 v[114:117], v[134:137], v[204:207], v[114:117]
	v_mfma_f32_16x16x32_bf16 v[110:113], v[164:167], v[204:207], v[110:113]
	v_mfma_f32_16x16x32_bf16 v[98:101], v[134:137], v[212:215], v[98:101]
	v_mfma_f32_16x16x32_bf16 v[94:97], v[164:167], v[212:215], v[94:97]
	v_mfma_f32_16x16x32_bf16 v[78:81], v[134:137], v[220:223], v[78:81]
	v_mfma_f32_16x16x32_bf16 v[74:77], v[164:167], v[220:223], v[74:77]
	s_setprio 0
	s_setprio 1
	v_mfma_f32_16x16x32_bf16 v[122:125], v[168:171], v[184:187], v[122:125]
	v_mfma_f32_16x16x32_bf16 v[118:121], v[176:179], v[184:187], v[118:121]
	v_mfma_f32_16x16x32_bf16 v[106:109], v[168:171], v[200:203], v[106:109]
	v_mfma_f32_16x16x32_bf16 v[102:105], v[176:179], v[200:203], v[102:105]
	v_mfma_f32_16x16x32_bf16 v[90:93], v[168:171], v[208:211], v[90:93]
	v_mfma_f32_16x16x32_bf16 v[86:89], v[176:179], v[208:211], v[86:89]
	v_mfma_f32_16x16x32_bf16 v[70:73], v[168:171], v[216:219], v[70:73]
	v_mfma_f32_16x16x32_bf16 v[66:69], v[176:179], v[216:219], v[66:69]
	v_mfma_f32_16x16x32_bf16 v[122:125], v[172:175], v[196:199], v[122:125]
	v_mfma_f32_16x16x32_bf16 v[118:121], v[180:183], v[196:199], v[118:121]
	v_mfma_f32_16x16x32_bf16 v[106:109], v[172:175], v[204:207], v[106:109]
	v_mfma_f32_16x16x32_bf16 v[102:105], v[180:183], v[204:207], v[102:105]
	v_mfma_f32_16x16x32_bf16 v[90:93], v[172:175], v[212:215], v[90:93]
	v_mfma_f32_16x16x32_bf16 v[86:89], v[180:183], v[212:215], v[86:89]
	v_mfma_f32_16x16x32_bf16 v[70:73], v[172:175], v[220:223], v[70:73]
	v_mfma_f32_16x16x32_bf16 v[66:69], v[180:183], v[220:223], v[66:69]
	s_setprio 0
	s_barrier
	s_add_i32 s31, s56, s27
	v_lshl_add_u64 v[224:225], s[38:39], 0, v[140:141]
	s_mov_b32 m0, s31
	ds_read_b128 v[184:187], v192 offset:16384
	ds_read_b128 v[196:199], v192 offset:17408
	ds_read_b128 v[200:203], v192 offset:18432
	ds_read_b128 v[204:207], v192 offset:19456
	ds_read_b128 v[208:211], v192 offset:20480
	ds_read_b128 v[212:215], v192 offset:21504
	ds_read_b128 v[216:219], v192 offset:22528
	ds_read_b128 v[220:223], v192 offset:23552
	global_load_lds_dwordx4 v[224:225], off
	s_add_i32 m0, s31, 0x2000
	s_add_u32 s42, s38, 0x40000
	v_lshl_add_u64 v[226:227], s[38:39], 0, v[144:145]
	s_addc_u32 s43, s39, 0
	s_add_i32 s31, s57, s27
	global_load_lds_dwordx4 v[226:227], off
	v_lshl_add_u64 v[228:229], s[42:43], 0, v[140:141]
	s_mov_b32 m0, s31
	v_lshl_add_u64 v[230:231], s[40:41], 0, v[142:143]
	global_load_lds_dwordx4 v[228:229], off
	v_lshl_add_u64 v[228:229], s[42:43], 0, v[144:145]
	s_add_i32 m0, s31, 0x2000
	s_nop 0
	global_load_lds_dwordx4 v[228:229], off
	v_lshl_add_u64 v[228:229], s[40:41], 0, v[138:139]
	s_waitcnt vmcnt(4)
	s_waitcnt lgkmcnt(0)
	s_barrier
; #define PG8_STAGE(bufoff, gbase, voff) do { _Pragma("unroll") for (int _i = 0; _i < 2; ++_i) \
;         __builtin_amdgcn_global_load_lds((const unsigned*)((const char*)(gbase) + (voff)[_i]), (PG8_LAS unsigned*)(lds + (bufoff) + ldsw + _i * 8192), 16, 0, 0); } while (0)
; #define PG8_LDA(dst, b, h) do { _Pragma("unroll") for (int m = 0; m < 4; ++m) _Pragma("unroll") for (int k = 0; k < 2; ++k) dst[m][k] = *(const PG8_LAS bf16x8*)(lds + PG8_SA(b, h) + aoff + m * 2048 + k * 1024); } while (0)
; #define PG8_LDB(dst, b, h) do { _Pragma("unroll") for (int n = 0; n < 2; ++n) _Pragma("unroll") for (int k = 0; k < 2; ++k) dst[n][k] = *(const PG8_LAS bf16x8*)(lds + PG8_SB(b, h) + boff + n * 2048 + k * 1024); } while (0)
; #define PG8_MMA(ai, bj, At, Bt) do { __builtin_amdgcn_s_setprio(1); _Pragma("unroll") for (int m = 0; m < 4; ++m) _Pragma("unroll") for (int n = 0; n < 2; ++n) _Pragma("unroll") for (int k = 0; k < 2; ++k) \
;         acc[ai][bj][m][n] = __builtin_amdgcn_mfma_f32_16x16x32_bf16(Bt[n][k], At[m][k], acc[ai][bj][m][n], 0, 0, 0); __builtin_amdgcn_s_setprio(0); } while (0)
; #define PG8_WAIT_V(n) asm volatile("s_waitcnt vmcnt(" #n ")" ::: "memory")
; #define PG8_WAIT_L(n) asm volatile("s_waitcnt lgkmcnt(" #n ")" ::: "memory")
; #define PG8_BAR __builtin_amdgcn_s_barrier()
; #define PG8_SCHED __builtin_amdgcn_sched_barrier(0)
; template <class Epi, class Sched, bool ALIGN_EPI = false, bool SP2 = false, bool HALFM = false>
; __device__ __forceinline__ void gemm_phase(PG8_LAS unsigned char* lds, const Gemm g, const Sched& S, const Epi& E) {
;     ...
;             PG8_WAIT_V(8); PG8_WAIT_L(0); PG8_BAR; if constexpr (!HALFM) { PG8_MMA(1, 0, At, B0); PG8_MMA(1, 1, At, B1); } PG8_BAR; PG8_SCHED;
;             PG8_LDB(B0, 1, 0); PG8_LDB(B1, 1, 1); PG8_SCHED; PG8_LDA(At, 1, 0); PG8_STAGE(PG8_SA(0, 1), a2 + hstep, voffA);
;             PG8_WAIT_V(8); PG8_WAIT_L(0); PG8_BAR; PG8_MMA(0, 0, At, B0); PG8_MMA(0, 1, At, B1); PG8_BAR; PG8_SCHED;
	s_setprio 1
	s_waitcnt lgkmcnt(0)
	v_mfma_f32_16x16x32_bf16 v[62:65], v[82:85], v[184:187], v[62:65]
	v_mfma_f32_16x16x32_bf16 v[58:61], v[160:163], v[184:187], v[58:61]
	v_mfma_f32_16x16x32_bf16 v[46:49], v[82:85], v[200:203], v[46:49]
	v_mfma_f32_16x16x32_bf16 v[42:45], v[160:163], v[200:203], v[42:45]
	v_mfma_f32_16x16x32_bf16 v[30:33], v[82:85], v[208:211], v[30:33]
	v_mfma_f32_16x16x32_bf16 v[26:29], v[160:163], v[208:211], v[26:29]
	v_mfma_f32_16x16x32_bf16 v[14:17], v[82:85], v[216:219], v[14:17]
	v_mfma_f32_16x16x32_bf16 v[10:13], v[160:163], v[216:219], v[10:13]
	v_mfma_f32_16x16x32_bf16 v[62:65], v[134:137], v[196:199], v[62:65]
	v_mfma_f32_16x16x32_bf16 v[58:61], v[164:167], v[196:199], v[58:61]
	v_mfma_f32_16x16x32_bf16 v[46:49], v[134:137], v[204:207], v[46:49]
	v_mfma_f32_16x16x32_bf16 v[42:45], v[164:167], v[204:207], v[42:45]
	v_mfma_f32_16x16x32_bf16 v[30:33], v[134:137], v[212:215], v[30:33]
	v_mfma_f32_16x16x32_bf16 v[26:29], v[164:167], v[212:215], v[26:29]
	v_mfma_f32_16x16x32_bf16 v[14:17], v[134:137], v[220:223], v[14:17]
	v_mfma_f32_16x16x32_bf16 v[10:13], v[164:167], v[220:223], v[10:13]
	s_setprio 0
	s_setprio 1
	v_mfma_f32_16x16x32_bf16 v[54:57], v[168:171], v[184:187], v[54:57]
	v_mfma_f32_16x16x32_bf16 v[50:53], v[176:179], v[184:187], v[50:53]
	v_mfma_f32_16x16x32_bf16 v[38:41], v[168:171], v[200:203], v[38:41]
	v_mfma_f32_16x16x32_bf16 v[34:37], v[176:179], v[200:203], v[34:37]
	v_mfma_f32_16x16x32_bf16 v[22:25], v[168:171], v[208:211], v[22:25]
	v_mfma_f32_16x16x32_bf16 v[18:21], v[176:179], v[208:211], v[18:21]
	v_mfma_f32_16x16x32_bf16 v[6:9], v[168:171], v[216:219], v[6:9]
	v_mfma_f32_16x16x32_bf16 v[2:5], v[176:179], v[216:219], v[2:5]
	v_mfma_f32_16x16x32_bf16 v[54:57], v[172:175], v[196:199], v[54:57]
	v_mfma_f32_16x16x32_bf16 v[50:53], v[180:183], v[196:199], v[50:53]
	v_mfma_f32_16x16x32_bf16 v[38:41], v[172:175], v[204:207], v[38:41]
	v_mfma_f32_16x16x32_bf16 v[34:37], v[180:183], v[204:207], v[34:37]
	v_mfma_f32_16x16x32_bf16 v[22:25], v[172:175], v[212:215], v[22:25]
	v_mfma_f32_16x16x32_bf16 v[18:21], v[180:183], v[212:215], v[18:21]
	v_mfma_f32_16x16x32_bf16 v[6:9], v[172:175], v[220:223], v[6:9]
	v_mfma_f32_16x16x32_bf16 v[2:5], v[180:183], v[220:223], v[2:5]
	s_setprio 0
	s_barrier
	s_add_i32 s31, 0, 0x18000
	s_add_i32 s42, 0, 0x1c000
	v_add_u32_e32 v164, s31, v188
	v_add_u32_e32 v180, s42, v188
	ds_read_b128 v[82:85], v164
	ds_read_b128 v[134:137], v164 offset:1024
	ds_read_b128 v[160:163], v164 offset:2048
	ds_read_b128 v[164:167], v164 offset:3072
	ds_read_b128 v[168:171], v180
	ds_read_b128 v[172:175], v180 offset:1024
	ds_read_b128 v[176:179], v180 offset:2048
	ds_read_b128 v[180:183], v180 offset:3072
	s_add_u32 s40, s40, 0x40000
	s_addc_u32 s41, s41, 0
	s_mov_b32 m0, s48
	v_lshl_add_u64 v[232:233], s[40:41], 0, v[138:139]
	ds_read_b128 v[184:187], v192 offset:32768
	ds_read_b128 v[196:199], v192 offset:33792
	ds_read_b128 v[200:203], v192 offset:34816
	ds_read_b128 v[204:207], v192 offset:35840
	ds_read_b128 v[208:211], v192 offset:36864
	ds_read_b128 v[212:215], v192 offset:37888
	ds_read_b128 v[216:219], v192 offset:38912
	ds_read_b128 v[220:223], v192 offset:39936
	global_load_lds_dwordx4 v[232:233], off
	v_lshl_add_u64 v[232:233], s[40:41], 0, v[142:143]
	s_mov_b32 m0, s49
	s_nop 0
	global_load_lds_dwordx4 v[232:233], off
	s_mov_b32 m0, s44
	s_nop 0
	global_load_lds_dwordx4 v[228:229], off
	s_mov_b32 m0, s45
	s_nop 0
	global_load_lds_dwordx4 v[230:231], off
	s_waitcnt vmcnt(10)
	s_waitcnt lgkmcnt(0)
	s_barrier
	s_setprio 1
	s_waitcnt lgkmcnt(0)
	v_mfma_f32_16x16x32_bf16 v[130:133], v[82:85], v[184:187], v[130:133]
	v_mfma_f32_16x16x32_bf16 v[126:129], v[160:163], v[184:187], v[126:129]
	v_mfma_f32_16x16x32_bf16 v[114:117], v[82:85], v[200:203], v[114:117]
	v_mfma_f32_16x16x32_bf16 v[110:113], v[160:163], v[200:203], v[110:113]
	v_mfma_f32_16x16x32_bf16 v[98:101], v[82:85], v[208:211], v[98:101]
	v_mfma_f32_16x16x32_bf16 v[94:97], v[160:163], v[208:211], v[94:97]
	v_mfma_f32_16x16x32_bf16 v[78:81], v[82:85], v[216:219], v[78:81]
	v_mfma_f32_16x16x32_bf16 v[74:77], v[160:163], v[216:219], v[74:77]
	v_mfma_f32_16x16x32_bf16 v[130:133], v[134:137], v[196:199], v[130:133]
	v_mfma_f32_16x16x32_bf16 v[126:129], v[164:167], v[196:199], v[126:129]
	v_mfma_f32_16x16x32_bf16 v[114:117], v[134:137], v[204:207], v[114:117]
	v_mfma_f32_16x16x32_bf16 v[110:113], v[164:167], v[204:207], v[110:113]
	v_mfma_f32_16x16x32_bf16 v[98:101], v[134:137], v[212:215], v[98:101]
	v_mfma_f32_16x16x32_bf16 v[94:97], v[164:167], v[212:215], v[94:97]
	v_mfma_f32_16x16x32_bf16 v[78:81], v[134:137], v[220:223], v[78:81]
	v_mfma_f32_16x16x32_bf16 v[74:77], v[164:167], v[220:223], v[74:77]
	s_setprio 0
	s_setprio 1
	v_mfma_f32_16x16x32_bf16 v[122:125], v[168:171], v[184:187], v[122:125]
	v_mfma_f32_16x16x32_bf16 v[118:121], v[176:179], v[184:187], v[118:121]
	v_mfma_f32_16x16x32_bf16 v[106:109], v[168:171], v[200:203], v[106:109]
	v_mfma_f32_16x16x32_bf16 v[102:105], v[176:179], v[200:203], v[102:105]
	v_mfma_f32_16x16x32_bf16 v[90:93], v[168:171], v[208:211], v[90:93]
	v_mfma_f32_16x16x32_bf16 v[86:89], v[176:179], v[208:211], v[86:89]
	v_mfma_f32_16x16x32_bf16 v[70:73], v[168:171], v[216:219], v[70:73]
	v_mfma_f32_16x16x32_bf16 v[66:69], v[176:179], v[216:219], v[66:69]
	v_mfma_f32_16x16x32_bf16 v[122:125], v[172:175], v[196:199], v[122:125]
	v_mfma_f32_16x16x32_bf16 v[118:121], v[180:183], v[196:199], v[118:121]
	v_mfma_f32_16x16x32_bf16 v[106:109], v[172:175], v[204:207], v[106:109]
	v_mfma_f32_16x16x32_bf16 v[102:105], v[180:183], v[204:207], v[102:105]
	v_mfma_f32_16x16x32_bf16 v[90:93], v[172:175], v[212:215], v[90:93]
	v_mfma_f32_16x16x32_bf16 v[86:89], v[180:183], v[212:215], v[86:89]
	v_mfma_f32_16x16x32_bf16 v[70:73], v[172:175], v[220:223], v[70:73]
	v_mfma_f32_16x16x32_bf16 v[66:69], v[180:183], v[220:223], v[66:69]
	s_setprio 0
	s_barrier
; #define PG8_STAGE(bufoff, gbase, voff) do { _Pragma("unroll") for (int _i = 0; _i < 2; ++_i) \
;         __builtin_amdgcn_global_load_lds((const unsigned*)((const char*)(gbase) + (voff)[_i]), (PG8_LAS unsigned*)(lds + (bufoff) + ldsw + _i * 8192), 16, 0, 0); } while (0)
; #define PG8_LDA(dst, b, h) do { _Pragma("unroll") for (int m = 0; m < 4; ++m) _Pragma("unroll") for (int k = 0; k < 2; ++k) dst[m][k] = *(const PG8_LAS bf16x8*)(lds + PG8_SA(b, h) + aoff + m * 2048 + k * 1024); } while (0)
; #define PG8_MMA(ai, bj, At, Bt) do { __builtin_amdgcn_s_setprio(1); _Pragma("unroll") for (int m = 0; m < 4; ++m) _Pragma("unroll") for (int n = 0; n < 2; ++n) _Pragma("unroll") for (int k = 0; k < 2; ++k) \
;         acc[ai][bj][m][n] = __builtin_amdgcn_mfma_f32_16x16x32_bf16(Bt[n][k], At[m][k], acc[ai][bj][m][n], 0, 0, 0); __builtin_amdgcn_s_setprio(0); } while (0)
; #define PG8_WAIT_V(n) asm volatile("s_waitcnt vmcnt(" #n ")" ::: "memory")
; #define PG8_WAIT_L(n) asm volatile("s_waitcnt lgkmcnt(" #n ")" ::: "memory")
; #define PG8_BAR __builtin_amdgcn_s_barrier()
; #define PG8_SCHED __builtin_amdgcn_sched_barrier(0)
; template <class Epi, class Sched, bool ALIGN_EPI = false, bool SP2 = false, bool HALFM = false>
; __device__ __forceinline__ void gemm_phase(PG8_LAS unsigned char* lds, const Gemm g, const Sched& S, const Epi& E) {
;     ...
;             PG8_LDA(At, 1, 1); PG8_STAGE(PG8_SB(1, 0), b3, voffB); PG8_STAGE(PG8_SB(1, 1), b3 + hstep, voffB); PG8_STAGE(PG8_SA(1, 0), a3, voffA);
;             PG8_WAIT_V(8); PG8_WAIT_L(0); PG8_BAR; if constexpr (!HALFM) { PG8_MMA(1, 0, At, B0); PG8_MMA(1, 1, At, B1); } PG8_BAR; PG8_SCHED;
	s_add_i32 s31, s31, s27
	v_lshl_add_u64 v[224:225], v[224:225], 0, s[20:21]
	s_mov_b32 m0, s31
	ds_read_b128 v[184:187], v192 offset:49152
	ds_read_b128 v[196:199], v192 offset:50176
	ds_read_b128 v[200:203], v192 offset:51200
	ds_read_b128 v[204:207], v192 offset:52224
	ds_read_b128 v[208:211], v192 offset:53248
	ds_read_b128 v[212:215], v192 offset:54272
	ds_read_b128 v[216:219], v192 offset:55296
	ds_read_b128 v[220:223], v192 offset:56320
	global_load_lds_dwordx4 v[224:225], off
	s_add_i32 m0, s31, 0x2000
	s_add_u32 s38, s38, 0x40080
	v_lshl_add_u64 v[224:225], v[226:227], 0, s[20:21]
	s_addc_u32 s39, s39, 0
	s_add_i32 s31, s42, s27
	global_load_lds_dwordx4 v[224:225], off
	v_lshl_add_u64 v[224:225], s[38:39], 0, v[140:141]
	s_mov_b32 m0, s31
	s_nop 0
	global_load_lds_dwordx4 v[224:225], off
	v_lshl_add_u64 v[224:225], s[38:39], 0, v[144:145]
	s_add_i32 m0, s31, 0x2000
	s_nop 0
	global_load_lds_dwordx4 v[224:225], off
	s_waitcnt vmcnt(4)
	s_waitcnt lgkmcnt(0)
	s_barrier
	s_setprio 1
	s_waitcnt lgkmcnt(0)
	v_mfma_f32_16x16x32_bf16 v[62:65], v[82:85], v[184:187], v[62:65]
	v_mfma_f32_16x16x32_bf16 v[58:61], v[160:163], v[184:187], v[58:61]
	v_mfma_f32_16x16x32_bf16 v[46:49], v[82:85], v[200:203], v[46:49]
	v_mfma_f32_16x16x32_bf16 v[42:45], v[160:163], v[200:203], v[42:45]
	v_mfma_f32_16x16x32_bf16 v[30:33], v[82:85], v[208:211], v[30:33]
	v_mfma_f32_16x16x32_bf16 v[26:29], v[160:163], v[208:211], v[26:29]
	v_mfma_f32_16x16x32_bf16 v[14:17], v[82:85], v[216:219], v[14:17]
	v_mfma_f32_16x16x32_bf16 v[10:13], v[160:163], v[216:219], v[10:13]
	v_mfma_f32_16x16x32_bf16 v[62:65], v[134:137], v[196:199], v[62:65]
	v_mfma_f32_16x16x32_bf16 v[58:61], v[164:167], v[196:199], v[58:61]
	v_mfma_f32_16x16x32_bf16 v[46:49], v[134:137], v[204:207], v[46:49]
	v_mfma_f32_16x16x32_bf16 v[42:45], v[164:167], v[204:207], v[42:45]
	v_mfma_f32_16x16x32_bf16 v[30:33], v[134:137], v[212:215], v[30:33]
	v_mfma_f32_16x16x32_bf16 v[26:29], v[164:167], v[212:215], v[26:29]
	v_mfma_f32_16x16x32_bf16 v[14:17], v[134:137], v[220:223], v[14:17]
	v_mfma_f32_16x16x32_bf16 v[10:13], v[164:167], v[220:223], v[10:13]
	s_setprio 0
	s_setprio 1
	v_mfma_f32_16x16x32_bf16 v[54:57], v[168:171], v[184:187], v[54:57]
	v_mfma_f32_16x16x32_bf16 v[50:53], v[176:179], v[184:187], v[50:53]
	v_mfma_f32_16x16x32_bf16 v[38:41], v[168:171], v[200:203], v[38:41]
	v_mfma_f32_16x16x32_bf16 v[34:37], v[176:179], v[200:203], v[34:37]
	v_mfma_f32_16x16x32_bf16 v[22:25], v[168:171], v[208:211], v[22:25]
	v_mfma_f32_16x16x32_bf16 v[18:21], v[176:179], v[208:211], v[18:21]
	v_mfma_f32_16x16x32_bf16 v[6:9], v[168:171], v[216:219], v[6:9]
	v_mfma_f32_16x16x32_bf16 v[2:5], v[176:179], v[216:219], v[2:5]
	v_mfma_f32_16x16x32_bf16 v[54:57], v[172:175], v[196:199], v[54:57]
	v_mfma_f32_16x16x32_bf16 v[50:53], v[180:183], v[196:199], v[50:53]
	v_mfma_f32_16x16x32_bf16 v[38:41], v[172:175], v[204:207], v[38:41]
	v_mfma_f32_16x16x32_bf16 v[34:37], v[180:183], v[204:207], v[34:37]
	v_mfma_f32_16x16x32_bf16 v[22:25], v[172:175], v[212:215], v[22:25]
	v_mfma_f32_16x16x32_bf16 v[18:21], v[180:183], v[212:215], v[18:21]
	v_mfma_f32_16x16x32_bf16 v[6:9], v[172:175], v[220:223], v[6:9]
	v_mfma_f32_16x16x32_bf16 v[2:5], v[180:183], v[220:223], v[2:5]
	s_setprio 0
	s_barrier
	s_add_i32 s29, s29, 2
	s_add_u32 s8, s8, 0x100
	s_addc_u32 s9, s9, 0
	s_add_u32 s5, s5, 0x100
	s_addc_u32 s11, s11, 0
	s_cmp_gt_u32 s29, 13
	s_cbranch_scc0 .LBB0_752
	s_and_b64 vcc, exec, s[22:23]
	s_cbranch_vccnz .LBB0_757
	s_cmp_gt_i32 s10, 45
	s_mov_b64 s[8:9], -1
	s_cbranch_scc1 .LBB0_758
